# removed the s_nop 7 padding ahead of the LDS waits at the three softmax heads (the wait already covers the MFMA-to-VALU distance)
# speedup vs baseline: 1.0130x; 1.0070x over previous
.Lat_loop:
	s_cmp_eq_u32 s35, 0
	s_cbranch_scc1 .Lat_yb_skip
	s_cmp_eq_u32 s22, 0
	s_cbranch_scc1 .Lat_yb_skip
	s_add_i32 s96, s22, -1
	s_cmp_gt_i32 s96, s25
	s_cbranch_scc1 .Lat_y_skip_b
	s_waitcnt lgkmcnt(0)
	v_mul_f32_e32 v66, v66, v162
	v_mul_f32_e32 v67, v67, v163
	v_mul_f32_e32 v68, v68, v164
	v_mul_f32_e32 v69, v69, v165
	v_mul_f32_e32 v70, v70, v166
	v_mul_f32_e32 v71, v71, v167
	v_mul_f32_e32 v72, v72, v168
	v_mul_f32_e32 v73, v73, v169
	v_mul_f32_e32 v74, v74, v170
	v_mul_f32_e32 v75, v75, v171
	v_mul_f32_e32 v76, v76, v172
	v_mul_f32_e32 v77, v77, v173
	v_mul_f32_e32 v78, v78, v174
	v_mul_f32_e32 v79, v79, v175
	v_mul_f32_e32 v80, v80, v176
	v_mul_f32_e32 v81, v81, v177
	v_mul_f32_e32 v82, v82, v178
	v_mul_f32_e32 v83, v83, v179
	v_mul_f32_e32 v84, v84, v180
	v_mul_f32_e32 v85, v85, v181
	v_mul_f32_e32 v86, v86, v182
	v_mul_f32_e32 v87, v87, v183
	v_mul_f32_e32 v88, v88, v184
	v_mul_f32_e32 v89, v89, v185
	v_mul_f32_e32 v90, v90, v186
	v_mul_f32_e32 v91, v91, v187
	v_mul_f32_e32 v92, v92, v188
	v_mul_f32_e32 v93, v93, v189
	v_mul_f32_e32 v94, v94, v190
	v_mul_f32_e32 v95, v95, v191
	v_mul_f32_e32 v96, v96, v192
	v_mul_f32_e32 v97, v97, v193
	s_cmp_lg_u32 s96, s25
	s_cbranch_scc1 .Lat_y_nogate_b
	v_add_u32_e32 v243, s38, v234
	v_lshlrev_b32_e32 v243, 11, v243
	v_lshl_add_u32 v243, v241, 3, v243
	global_load_dwordx2 v[162:163], v243, s[6:7] offset:0
	global_load_dwordx2 v[164:165], v243, s[6:7] offset:16
	global_load_dwordx2 v[166:167], v243, s[6:7] offset:32
	global_load_dwordx2 v[168:169], v243, s[6:7] offset:48
	global_load_dwordx2 v[170:171], v243, s[6:7] offset:64
	global_load_dwordx2 v[172:173], v243, s[6:7] offset:80
	global_load_dwordx2 v[174:175], v243, s[6:7] offset:96
	global_load_dwordx2 v[176:177], v243, s[6:7] offset:112
	global_load_dwordx2 v[178:179], v243, s[6:7] offset:128
	global_load_dwordx2 v[180:181], v243, s[6:7] offset:144
	global_load_dwordx2 v[182:183], v243, s[6:7] offset:160
	global_load_dwordx2 v[184:185], v243, s[6:7] offset:176
	global_load_dwordx2 v[186:187], v243, s[6:7] offset:192
	global_load_dwordx2 v[188:189], v243, s[6:7] offset:208
	global_load_dwordx2 v[190:191], v243, s[6:7] offset:224
	global_load_dwordx2 v[192:193], v243, s[6:7] offset:240

.Lat_nosq13:
.Lat_x_nopf:
	s_cmp_lg_u32 s35, 0
	s_cbranch_scc1 .Lat_ya_skip
	s_mov_b32 s96, s22
	s_cmp_gt_i32 s96, s25
	s_cbranch_scc1 .Lat_y_skip_a
	s_waitcnt lgkmcnt(0)
	v_mul_f32_e32 v66, v66, v162
	v_mul_f32_e32 v67, v67, v163
	v_mul_f32_e32 v68, v68, v164
	v_mul_f32_e32 v69, v69, v165
	v_mul_f32_e32 v70, v70, v166
	v_mul_f32_e32 v71, v71, v167
	v_mul_f32_e32 v72, v72, v168
	v_mul_f32_e32 v73, v73, v169
	v_mul_f32_e32 v74, v74, v170
	v_mul_f32_e32 v75, v75, v171
	v_mul_f32_e32 v76, v76, v172
	v_mul_f32_e32 v77, v77, v173
	v_mul_f32_e32 v78, v78, v174
	v_mul_f32_e32 v79, v79, v175
	v_mul_f32_e32 v80, v80, v176
	v_mul_f32_e32 v81, v81, v177
	v_mul_f32_e32 v82, v82, v178
	v_mul_f32_e32 v83, v83, v179
	v_mul_f32_e32 v84, v84, v180
	v_mul_f32_e32 v85, v85, v181
	v_mul_f32_e32 v86, v86, v182
	v_mul_f32_e32 v87, v87, v183
	v_mul_f32_e32 v88, v88, v184
	v_mul_f32_e32 v89, v89, v185
	v_mul_f32_e32 v90, v90, v186
	v_mul_f32_e32 v91, v91, v187
	v_mul_f32_e32 v92, v92, v188
	v_mul_f32_e32 v93, v93, v189
	v_mul_f32_e32 v94, v94, v190
	v_mul_f32_e32 v95, v95, v191
	v_mul_f32_e32 v96, v96, v192
	v_mul_f32_e32 v97, v97, v193
	s_cmp_lg_u32 s96, s25
	s_cbranch_scc1 .Lat_y_nogate_a
	v_add_u32_e32 v243, s38, v234
	v_lshlrev_b32_e32 v243, 11, v243
	v_lshl_add_u32 v243, v241, 3, v243
	global_load_dwordx2 v[162:163], v243, s[6:7] offset:0
	global_load_dwordx2 v[164:165], v243, s[6:7] offset:16
	global_load_dwordx2 v[166:167], v243, s[6:7] offset:32
	global_load_dwordx2 v[168:169], v243, s[6:7] offset:48
	global_load_dwordx2 v[170:171], v243, s[6:7] offset:64
	global_load_dwordx2 v[172:173], v243, s[6:7] offset:80
	global_load_dwordx2 v[174:175], v243, s[6:7] offset:96
	global_load_dwordx2 v[176:177], v243, s[6:7] offset:112
	global_load_dwordx2 v[178:179], v243, s[6:7] offset:128
	global_load_dwordx2 v[180:181], v243, s[6:7] offset:144
	global_load_dwordx2 v[182:183], v243, s[6:7] offset:160
	global_load_dwordx2 v[184:185], v243, s[6:7] offset:176
	global_load_dwordx2 v[186:187], v243, s[6:7] offset:192
	global_load_dwordx2 v[188:189], v243, s[6:7] offset:208
	global_load_dwordx2 v[190:191], v243, s[6:7] offset:224
	global_load_dwordx2 v[192:193], v243, s[6:7] offset:240

.Lat_yz:
	s_add_i32 s22, s22, 1
	s_add_i32 s24, s24, 1
	s_cmp_eq_u32 s24, 3
	s_cselect_b32 s24, 0, s24
	s_cmp_lt_u32 s22, s23
	s_cbranch_scc1 .Lat_loop
	s_cmp_eq_u32 s35, 0
	s_cbranch_scc1 .Lat_yc_skip
	s_add_i32 s96, s23, -1
	s_cmp_gt_i32 s96, s25
	s_cbranch_scc1 .Lat_y_skip_c
	s_waitcnt lgkmcnt(0)
	v_mul_f32_e32 v66, v66, v162
	v_mul_f32_e32 v67, v67, v163
	v_mul_f32_e32 v68, v68, v164
	v_mul_f32_e32 v69, v69, v165
	v_mul_f32_e32 v70, v70, v166
	v_mul_f32_e32 v71, v71, v167
	v_mul_f32_e32 v72, v72, v168
	v_mul_f32_e32 v73, v73, v169
	v_mul_f32_e32 v74, v74, v170
	v_mul_f32_e32 v75, v75, v171
	v_mul_f32_e32 v76, v76, v172
	v_mul_f32_e32 v77, v77, v173
	v_mul_f32_e32 v78, v78, v174
	v_mul_f32_e32 v79, v79, v175
	v_mul_f32_e32 v80, v80, v176
	v_mul_f32_e32 v81, v81, v177
	v_mul_f32_e32 v82, v82, v178
	v_mul_f32_e32 v83, v83, v179
	v_mul_f32_e32 v84, v84, v180
	v_mul_f32_e32 v85, v85, v181
	v_mul_f32_e32 v86, v86, v182
	v_mul_f32_e32 v87, v87, v183
	v_mul_f32_e32 v88, v88, v184
	v_mul_f32_e32 v89, v89, v185
	v_mul_f32_e32 v90, v90, v186
	v_mul_f32_e32 v91, v91, v187
	v_mul_f32_e32 v92, v92, v188
	v_mul_f32_e32 v93, v93, v189
	v_mul_f32_e32 v94, v94, v190
	v_mul_f32_e32 v95, v95, v191
	v_mul_f32_e32 v96, v96, v192
	v_mul_f32_e32 v97, v97, v193
	s_cmp_lg_u32 s96, s25
	s_cbranch_scc1 .Lat_y_nogate_c
	v_add_u32_e32 v243, s38, v234
	v_lshlrev_b32_e32 v243, 11, v243
	v_lshl_add_u32 v243, v241, 3, v243
	global_load_dwordx2 v[162:163], v243, s[6:7] offset:0
	global_load_dwordx2 v[164:165], v243, s[6:7] offset:16
	global_load_dwordx2 v[166:167], v243, s[6:7] offset:32
	global_load_dwordx2 v[168:169], v243, s[6:7] offset:48
	global_load_dwordx2 v[170:171], v243, s[6:7] offset:64
	global_load_dwordx2 v[172:173], v243, s[6:7] offset:80
	global_load_dwordx2 v[174:175], v243, s[6:7] offset:96
	global_load_dwordx2 v[176:177], v243, s[6:7] offset:112
	global_load_dwordx2 v[178:179], v243, s[6:7] offset:128
	global_load_dwordx2 v[180:181], v243, s[6:7] offset:144
	global_load_dwordx2 v[182:183], v243, s[6:7] offset:160
	global_load_dwordx2 v[184:185], v243, s[6:7] offset:176
	global_load_dwordx2 v[186:187], v243, s[6:7] offset:192
	global_load_dwordx2 v[188:189], v243, s[6:7] offset:208
	global_load_dwordx2 v[190:191], v243, s[6:7] offset:224
	global_load_dwordx2 v[192:193], v243, s[6:7] offset:240
